# neighbourhood attention: rpb row loads issued together; 16 bias LDS reads per latent tile hoisted out of the exec-masked blocks
# speedup vs baseline: 1.0015x; 1.0015x over previous
.LBB0_414:
	s_andn2_b64 vcc, exec, s[0:1]
	s_cbranch_vccnz .LBB0_478
	s_bfe_u32 s14, s53, 0x30003
	s_or_b32 s0, s3, s14
	s_mul_i32 s96, s0, 0x744
	v_lshl_add_u64 v[2:3], v[148:149], 0, s[96:97]
	global_load_dword v232, v[2:3], off
	global_load_dword v233, v[2:3], off offset:256
	global_load_dword v234, v[2:3], off offset:512
	global_load_dword v235, v[2:3], off offset:768
	global_load_dword v236, v[2:3], off offset:1024
	global_load_dword v237, v[2:3], off offset:1280
	global_load_dword v238, v[2:3], off offset:1536
	v_cmp_gt_u32_e32 vcc, 0xffffffd1, v172
	s_and_saveexec_b64 s[0:1], vcc
	global_load_dword v239, v[2:3], off offset:1792
	s_or_b64 exec, exec, s[0:1]
	s_waitcnt vmcnt(0)
	v_mul_f32_e32 v232, 0x3fb8aa3b, v232
	ds_write_b32 v173, v232
	v_mul_f32_e32 v233, 0x3fb8aa3b, v233
	ds_write_b32 v173, v233 offset:256
	v_mul_f32_e32 v234, 0x3fb8aa3b, v234
	ds_write_b32 v173, v234 offset:512
	v_mul_f32_e32 v235, 0x3fb8aa3b, v235
	ds_write_b32 v173, v235 offset:768
	v_mul_f32_e32 v236, 0x3fb8aa3b, v236
	ds_write_b32 v173, v236 offset:1024
	v_mul_f32_e32 v237, 0x3fb8aa3b, v237
	ds_write_b32 v173, v237 offset:1280
	v_mul_f32_e32 v238, 0x3fb8aa3b, v238
	ds_write_b32 v173, v238 offset:1536
	s_and_saveexec_b64 s[0:1], vcc
	v_mul_f32_e32 v239, 0x3fb8aa3b, v239
	ds_write_b32 v173, v239 offset:1792
	s_or_b64 exec, exec, s[0:1]
	s_lshl_b32 s0, s53, 2
	s_add_i32 s1, s53, 0xffffff00
	s_and_b32 s0, s0, 28
	s_lshr_b32 s1, s1, 6
	v_add_u32_e32 v105, s0, v169
	s_lshl_b32 s57, s1, 11
	v_lshl_or_b32 v0, v105, 6, v170
	s_add_i32 s10, s57, 0x1000
	v_add_u32_e32 v98, s10, v0
	v_sub_u32_e64 v0, s0, 1 clamp
	v_sub_u32_e64 v36, s0, 4 clamp
	v_readfirstlane_b32 s0, v0
	s_min_u32 s0, s0, 24
	s_lshl_b32 s96, s14, 7
	s_add_u32 s4, s94, s96
	s_addc_u32 s5, s95, 0
	s_mul_i32 s8, s14, 0x1c0000
	v_readlane_b32 s36, v253, 17
	v_readlane_b32 s37, v253, 18
	s_add_u32 s8, s36, s8
	v_readfirstlane_b32 s11, v36
	s_addc_u32 s9, s37, 0
	s_sub_i32 s52, s0, s11
	v_mov_b32_e32 v38, v206
	s_add_i32 s63, s52, 8
	s_lshl_b32 s64, s1, 9
	s_movk_i32 s0, 0x3800
	v_ashrrev_i32_e32 v0, 3, v38
	v_lshrrev_b32_e32 v4, 4, v38
	v_ashrrev_i32_e32 v99, 31, v98
	s_lshl_b32 s12, s11, 6
	s_addk_i32 s64, 0x3000
	v_xor_b32_e32 v4, v4, v38
	v_mul_lo_u32 v5, v0, s0
	s_lshl_b32 s0, s63, 6
	v_lshlrev_b64 v[2:3], 10, v[98:99]
	s_or_b32 s62, s12, s10
	v_lshlrev_b32_e32 v4, 3, v4
	s_sub_i32 s0, s64, s0
	v_lshl_add_u64 v[2:3], s[92:93], 0, v[2:3]
	v_and_b32_e32 v104, 31, v38
	v_and_b32_e32 v4, 56, v4
	v_lshlrev_b32_e32 v0, 10, v0
	s_cmp_gt_i32 s52, -8
	v_lshl_add_u64 v[2:3], v[2:3], 0, s[96:97]
	v_bfe_u32 v37, v38, 5, 1
	v_or_b32_e32 v5, v4, v5
	v_lshl_or_b32 v4, v4, 1, v0
	v_lshlrev_b32_e32 v0, 10, v104
	s_cselect_b32 s96, s62, s0
	v_lshl_add_u64 v[2:3], v[2:3], 0, v[0:1]
	v_lshlrev_b32_e32 v0, 4, v37
	s_lshl_b64 s[10:11], s[96:97], 10
	v_lshl_add_u64 v[2:3], v[2:3], 0, v[0:1]
	v_lshlrev_b32_e32 v107, 4, v38
	s_add_u32 s10, s4, s10
	global_load_dwordx4 v[82:85], v[2:3], off
	global_load_dwordx4 v[86:89], v[2:3], off offset:32
	global_load_dwordx4 v[90:93], v[2:3], off offset:64
	global_load_dwordx4 v[94:97], v[2:3], off offset:96
	s_addc_u32 s11, s5, s11
	s_lshl_b64 s[12:13], s[96:97], 1
	v_readfirstlane_b32 s1, v107
	v_add_u32_e32 v0, 0x2000, v107
	s_add_u32 s12, s8, s12
	s_mov_b32 m0, s1
	v_readfirstlane_b32 s1, v0
	v_lshlrev_b32_e32 v34, 1, v5
	s_addc_u32 s13, s9, s13
	global_load_lds_dwordx4 v4, s[10:11]
	s_mov_b32 m0, s1
	v_mov_b32_e32 v0, v4
	global_load_lds_dwordx4 v34, s[12:13]
	s_cmp_lt_i32 s52, -14
	v_mov_b32_e32 v35, v1
	v_readlane_b32 s38, v253, 19
	v_readlane_b32 s39, v253, 20
	v_readlane_b32 s40, v253, 21
	v_readlane_b32 s41, v253, 22
	v_readlane_b32 s42, v253, 23
	v_readlane_b32 s43, v253, 24
	v_readlane_b32 s44, v253, 25
	v_readlane_b32 s45, v253, 26
	v_readlane_b32 s46, v253, 27
	v_readlane_b32 s47, v253, 28
	v_readlane_b32 s48, v253, 29
	v_readlane_b32 s49, v253, 30
	v_readlane_b32 s50, v253, 31
	v_readlane_b32 s51, v253, 32
	s_cbranch_scc1 .LBB0_419
	s_cmp_gt_i32 s52, -7
	s_cselect_b32 s10, s62, s0
	s_add_i32 s96, s10, 64
	s_lshl_b64 s[12:13], s[96:97], 10
	s_add_u32 s12, s4, s12
	s_mov_b32 s11, s97
	s_addc_u32 s13, s5, s13
	s_lshl_b64 s[10:11], s[10:11], 1
	v_add_u32_e32 v4, 0x4000, v107
	s_add_u32 s10, s8, s10
	v_readfirstlane_b32 s1, v4
	s_addc_u32 s11, s9, s11
	v_lshl_add_u64 v[2:3], s[12:13], 0, v[0:1]
	s_mov_b32 m0, s1
	v_add_u32_e32 v4, 0x6000, v107
	global_load_lds_dwordx4 v[2:3], off
	v_lshl_add_u64 v[2:3], s[10:11], 0, v[34:35]
	s_mov_b64 s[10:11], 0x80
	v_readfirstlane_b32 s1, v4
	v_lshl_add_u64 v[2:3], v[2:3], 0, s[10:11]
	s_mov_b32 m0, s1
	s_nop 0
	global_load_lds_dwordx4 v[2:3], off

.Lprio_16:
	s_and_b32 s4, s56, 0xc000
	v_or_b32_e32 v38, s4, v110
	v_or_b32_e32 v204, s4, v111
	v_or_b32_e32 v205, s4, v112
	v_or_b32_e32 v248, s4, v113
	ds_read_b128 v[196:199], v38
	ds_read_b128 v[200:203], v204
	ds_read_b128 v[232:235], v38 offset:4096
	ds_read_b128 v[236:239], v204 offset:4096
	ds_read_b128 v[240:243], v205
	s_andn2_b64 vcc, exec, s[10:11]
	s_waitcnt lgkmcnt(4)
	v_mfma_f32_32x32x16_bf16 v[50:65], v[196:199], v[82:85], 0
	ds_read_b128 v[244:247], v205 offset:4096
	s_waitcnt lgkmcnt(4)
	v_mfma_f32_32x32x16_bf16 v[50:65], v[200:203], v[86:89], v[50:65]
	ds_read_b128 v[196:199], v248
	s_waitcnt lgkmcnt(4)
	v_mfma_f32_32x32x16_bf16 v[34:49], v[232:235], v[82:85], 0
	ds_read_b128 v[200:203], v248 offset:4096
	s_waitcnt lgkmcnt(4)
	v_mfma_f32_32x32x16_bf16 v[34:49], v[236:239], v[86:89], v[34:49]
	s_waitcnt lgkmcnt(3)
	v_mfma_f32_32x32x16_bf16 v[50:65], v[240:243], v[90:93], v[50:65]
	s_waitcnt lgkmcnt(2)
	v_mfma_f32_32x32x16_bf16 v[34:49], v[244:247], v[90:93], v[34:49]
	s_waitcnt lgkmcnt(1)
	v_mfma_f32_32x32x16_bf16 v[50:65], v[196:199], v[94:97], v[50:65]
	s_waitcnt lgkmcnt(0)
	v_mfma_f32_32x32x16_bf16 v[34:49], v[200:203], v[94:97], v[34:49]
	s_nop 1
	s_cbranch_vccnz .LBB0_474
	s_lshl_b32 s0, s5, 6
	s_sub_i32 s1, s54, s57
	s_add_i32 s0, s1, s0
	s_addk_i32 s0, 0xf000
	s_ashr_i32 s0, s0, 6
	v_sub_u32_e32 v66, s0, v105
	s_movk_i32 s0, 0x7c
	v_mul_lo_u32 v66, v66, s0
	v_add_u32_e32 v117, v114, v66
	ds_read_b32 v116, v117 offset:1056
	ds_read_b32 v196, v117 offset:928
	ds_read_b32 v197, v117 offset:932
	ds_read_b32 v198, v117 offset:936
	ds_read_b32 v199, v117 offset:940
	ds_read_b32 v200, v117 offset:960
	ds_read_b32 v201, v117 offset:964
	ds_read_b32 v202, v117 offset:968
	ds_read_b32 v203, v117 offset:972
	ds_read_b32 v204, v117 offset:992
	ds_read_b32 v205, v117 offset:996
	ds_read_b32 v232, v117 offset:1000
	ds_read_b32 v233, v117 offset:1004
	ds_read_b32 v234, v117 offset:1024
	ds_read_b32 v235, v117 offset:1028
	ds_read_b32 v236, v117 offset:1032
	ds_read_b32 v237, v117 offset:1036
	s_waitcnt lgkmcnt(0)
	v_mov_b32_e32 v67, 0xff800000
	v_mov_b32_e32 v66, 0xff800000
	s_and_saveexec_b64 s[0:1], s[40:41]
	s_cbranch_execz .LBB0_443
	v_add_f32_e32 v66, v50, v196
.LBB0_443:
	s_or_b64 exec, exec, s[0:1]
	ds_read_b32 v50, v117 offset:1060
	s_and_saveexec_b64 s[0:1], s[44:45]
	s_cbranch_execz .LBB0_445
	v_add_f32_e32 v67, v51, v197
.LBB0_445:
	s_or_b64 exec, exec, s[0:1]
	ds_read_b32 v51, v117 offset:1064
	v_mov_b32_e32 v69, 0xff800000
	v_mov_b32_e32 v68, 0xff800000
	s_and_saveexec_b64 s[0:1], s[48:49]
	s_cbranch_execz .LBB0_447
	v_add_f32_e32 v68, v52, v198
.LBB0_447:
	s_or_b64 exec, exec, s[0:1]
	ds_read_b32 v52, v117 offset:1068
	s_mov_b64 s[0:1], exec
	v_readlane_b32 s10, v254, 59
	v_readlane_b32 s11, v254, 60
	s_and_b64 s[10:11], s[0:1], s[10:11]
	s_mov_b64 exec, s[10:11]
	s_cbranch_execz .LBB0_449
	v_add_f32_e32 v69, v53, v199
.LBB0_449:
	s_or_b64 exec, exec, s[0:1]
	ds_read_b32 v53, v117 offset:1088
	v_mov_b32_e32 v71, 0xff800000
	v_mov_b32_e32 v70, 0xff800000
	s_mov_b64 s[0:1], exec
	v_readlane_b32 s10, v254, 63
	v_readlane_b32 s11, v255, 0
	s_and_b64 s[10:11], s[0:1], s[10:11]
	s_mov_b64 exec, s[10:11]
	s_cbranch_execz .LBB0_451
	v_add_f32_e32 v70, v54, v200
.LBB0_451:
	s_or_b64 exec, exec, s[0:1]
	ds_read_b32 v54, v117 offset:1092
	s_mov_b64 s[0:1], exec
	v_readlane_b32 s10, v255, 3
	v_readlane_b32 s11, v255, 4
	s_and_b64 s[10:11], s[0:1], s[10:11]
	s_mov_b64 exec, s[10:11]
	s_cbranch_execz .LBB0_453
	v_add_f32_e32 v71, v55, v201
.LBB0_453:
	s_or_b64 exec, exec, s[0:1]
	ds_read_b32 v55, v117 offset:1096
	v_mov_b32_e32 v73, 0xff800000
	v_mov_b32_e32 v72, 0xff800000
	s_mov_b64 s[0:1], exec
	v_readlane_b32 s10, v255, 7
	v_readlane_b32 s11, v255, 8
	s_and_b64 s[10:11], s[0:1], s[10:11]
	s_mov_b64 exec, s[10:11]
	s_cbranch_execz .LBB0_455
	v_add_f32_e32 v72, v56, v202
.LBB0_455:
	s_or_b64 exec, exec, s[0:1]
	ds_read_b32 v56, v117 offset:1100
	s_mov_b64 s[0:1], exec
	v_readlane_b32 s10, v255, 11
	v_readlane_b32 s11, v255, 12
	s_and_b64 s[10:11], s[0:1], s[10:11]
	s_mov_b64 exec, s[10:11]
	s_cbranch_execz .LBB0_457
	v_add_f32_e32 v73, v57, v203
.LBB0_457:
	s_or_b64 exec, exec, s[0:1]
	ds_read_b32 v57, v117 offset:1120
	v_mov_b32_e32 v75, 0xff800000
	v_mov_b32_e32 v74, 0xff800000
	s_mov_b64 s[0:1], exec
	v_readlane_b32 s10, v255, 15
	v_readlane_b32 s11, v255, 16
	s_and_b64 s[10:11], s[0:1], s[10:11]
	s_mov_b64 exec, s[10:11]
	s_cbranch_execz .LBB0_459
	v_add_f32_e32 v74, v58, v204
.LBB0_459:
	s_or_b64 exec, exec, s[0:1]
	ds_read_b32 v58, v117 offset:1124
	s_mov_b64 s[0:1], exec
	v_readlane_b32 s10, v255, 19
	v_readlane_b32 s11, v255, 20
	s_and_b64 s[10:11], s[0:1], s[10:11]
	s_mov_b64 exec, s[10:11]
	s_cbranch_execz .LBB0_461
	v_add_f32_e32 v75, v59, v205
.LBB0_461:
	s_or_b64 exec, exec, s[0:1]
	ds_read_b32 v59, v117 offset:1128
	v_mov_b32_e32 v77, 0xff800000
	v_mov_b32_e32 v76, 0xff800000
	s_mov_b64 s[0:1], exec
	v_readlane_b32 s10, v255, 23
	v_readlane_b32 s11, v255, 24
	s_and_b64 s[10:11], s[0:1], s[10:11]
	s_mov_b64 exec, s[10:11]
	s_cbranch_execz .LBB0_463
	v_add_f32_e32 v76, v60, v232
.LBB0_463:
	s_or_b64 exec, exec, s[0:1]
	ds_read_b32 v60, v117 offset:1132
	s_mov_b64 s[0:1], exec
	v_readlane_b32 s10, v255, 27
	v_readlane_b32 s11, v255, 28
	s_and_b64 s[10:11], s[0:1], s[10:11]
	s_mov_b64 exec, s[10:11]
	s_cbranch_execz .LBB0_465
	v_add_f32_e32 v77, v61, v233
.LBB0_465:
	s_or_b64 exec, exec, s[0:1]
	ds_read_b32 v61, v117 offset:1152
	v_mov_b32_e32 v79, 0xff800000
	v_mov_b32_e32 v78, 0xff800000
	s_mov_b64 s[0:1], exec
	v_readlane_b32 s10, v255, 31
	v_readlane_b32 s11, v255, 32
	s_and_b64 s[10:11], s[0:1], s[10:11]
	s_mov_b64 exec, s[10:11]
	s_cbranch_execz .LBB0_467
	v_add_f32_e32 v78, v62, v234
.LBB0_467:
	s_or_b64 exec, exec, s[0:1]
	ds_read_b32 v62, v117 offset:1156
	s_mov_b64 s[0:1], exec
	v_readlane_b32 s10, v255, 35
	v_readlane_b32 s11, v255, 36
	s_and_b64 s[10:11], s[0:1], s[10:11]
	s_mov_b64 exec, s[10:11]
	s_cbranch_execz .LBB0_469
	v_add_f32_e32 v79, v63, v235
.LBB0_469:
	s_or_b64 exec, exec, s[0:1]
	ds_read_b32 v118, v117 offset:1160
	v_mov_b32_e32 v81, 0xff800000
	v_mov_b32_e32 v80, 0xff800000
	s_and_saveexec_b64 s[0:1], s[14:15]
	s_cbranch_execz .LBB0_471
	v_add_f32_e32 v80, v64, v236
.LBB0_471:
	s_or_b64 exec, exec, s[0:1]
	ds_read_b32 v63, v117 offset:1164
	s_and_saveexec_b64 s[0:1], s[8:9]
	s_cbranch_execz .LBB0_473
	v_add_f32_e32 v81, v65, v237
